# NA-local attention: relative-position-bias table staged in LDS, per-element gathers are LDS reads
# speedup vs baseline: 1.0139x; 1.0048x over previous
.LBB0_451:
	s_and_b64 vcc, exec, s[0:1]
	s_cbranch_vccz .LBB0_494
	s_add_i32 s0, s84, 0xfffffc00
	s_lshr_b32 s2, s0, 9
	s_and_b32 s3, s84, 63
	s_lshl_b32 s0, s2, 12
	v_med3_u32 v80, s3, 4, 60
	s_addk_i32 s0, 0x2000
	s_lshl_b32 s1, s3, 6
	s_or_b32 s50, s0, s1
	v_readfirstlane_b32 s1, v80
	s_lshl_b32 s1, s1, 6
	s_or_b32 s0, s1, s0
	s_bfe_u32 s8, s84, 0x30006
	s_add_i32 s9, s0, 0xffffff00
	s_mul_i32 s1, s50, 0x1a00
	s_mul_hi_u32 s0, s50, 0x1a00
	s_add_u32 s1, s44, s1
	s_addc_u32 s4, s45, s0
	s_lshl_b32 s96, s8, 6
	s_lshl_b32 s10, s8, 7
	s_add_u32 s0, s1, s10
	v_mov_b32_e32 v10, v228
	s_addc_u32 s1, s4, 0
	s_lshl_b32 s2, s2, 1
	v_ashrrev_i32_e32 v0, 2, v10
	v_bfe_u32 v11, v10, 4, 2
	v_and_b32_e32 v13, -16, v0
	v_bfi_b32 v56, -16, v0, v10
	v_mov_b64_e32 v[0:1], s[0:1]
	v_mad_i64_i32 v[0:1], s[0:1], v56, s70, v[0:1]
	v_lshlrev_b32_e32 v196, 4, v11
	v_lshl_add_u64 v[0:1], v[0:1], 0, v[196:197]
	global_load_dwordx4 v[20:23], v[0:1], off
	global_load_dwordx4 v[16:19], v[0:1], off offset:64
	v_ashrrev_i32_e32 v0, 31, v10
	v_lshrrev_b32_e32 v0, 29, v0
	v_add_u32_e32 v4, v10, v0
	v_readlane_b32 s4, v254, 52
	v_ashrrev_i32_e32 v60, 3, v4
	v_and_b32_e32 v4, -8, v4
	s_add_i32 s4, s2, s4
	s_mov_b32 s5, s51
	v_sub_u32_e32 v40, v10, v4
	s_lshl_b64 s[4:5], s[4:5], 19
	v_readlane_b32 s6, v253, 5
	v_lshlrev_b32_e32 v4, 3, v40
	v_readlane_b32 s7, v253, 6
	s_add_u32 s56, s6, s4
	v_ashrrev_i32_e32 v5, 31, v4
	v_add_u32_e32 v8, 0x100, v10
	s_addc_u32 s57, s7, s5
	v_lshlrev_b64 v[62:63], 1, v[4:5]
	v_ashrrev_i32_e32 v4, 31, v8
	s_add_u32 s6, s56, s10
	v_lshrrev_b32_e32 v4, 29, v4
	s_addc_u32 s7, s57, 0
	v_readlane_b32 s12, v253, 3
	v_add_u32_e32 v9, v8, v4
	v_readlane_b32 s13, v253, 4
	s_add_u32 s64, s12, s4
	v_ashrrev_i32_e32 v64, 3, v9
	v_and_b32_e32 v9, -8, v9
	s_addc_u32 s65, s13, s5
	v_ashrrev_i32_e32 v61, 31, v60
	v_sub_u32_e32 v41, v8, v9
	s_add_u32 s4, s64, s10
	v_lshlrev_b64 v[0:1], 10, v[60:61]
	v_ashrrev_i32_e32 v65, 31, v64
	v_lshlrev_b32_e32 v8, 3, v41
	s_addc_u32 s5, s65, 0
	v_lshl_add_u64 v[2:3], s[6:7], 0, v[0:1]
	v_lshlrev_b64 v[4:5], 10, v[64:65]
	v_ashrrev_i32_e32 v9, 31, v8
	v_lshl_add_u64 v[2:3], v[2:3], 0, v[62:63]
	v_lshl_add_u64 v[6:7], s[6:7], 0, v[4:5]
	v_lshlrev_b64 v[66:67], 1, v[8:9]
	v_lshl_add_u64 v[0:1], s[4:5], 0, v[0:1]
	v_lshl_add_u64 v[6:7], v[6:7], 0, v[66:67]
	global_load_dwordx4 v[28:31], v[2:3], off
	global_load_dwordx4 v[24:27], v[6:7], off
	v_lshl_add_u64 v[0:1], v[0:1], 0, v[62:63]
	v_lshl_add_u64 v[2:3], s[4:5], 0, v[4:5]
	v_lshl_add_u64 v[2:3], v[2:3], 0, v[66:67]
	global_load_dwordx4 v[36:39], v[0:1], off
	global_load_dwordx4 v[32:35], v[2:3], off
	s_mul_hi_u32 s2, s9, 0x1a00
	s_mulk_i32 s9, 0x1a00
	s_add_u32 s9, s44, s9
	s_addc_u32 s2, s45, s2
	s_add_u32 s60, s9, 0x400
	s_addc_u32 s61, s2, 0
	s_add_u32 s62, s9, 0x800
	s_addc_u32 s63, s2, 0
	v_readlane_b32 s2, v254, 57
	s_or_b32 s2, s8, s2
	s_mul_i32 s8, s2, 0x1d1
	s_mov_b32 s9, s51
	v_med3_i32 v14, v56, 8, 56
	v_lshlrev_b32_e32 v58, 2, v11
	s_lshl_b64 s[8:9], s[8:9], 2
	v_readlane_b32 s12, v252, 29
	v_add_u32_e32 v15, -8, v14
	v_add_u32_e32 v0, 8, v14
	s_movk_i32 s0, 0xa0
	v_or_b32_e32 v79, 16, v58
	v_readlane_b32 s13, v252, 30
	v_readlane_b32 s24, v252, 41
	v_readlane_b32 s25, v252, 42
	s_add_u32 s54, s12, s8
	v_mul_lo_u32 v85, v56, s0
	v_mul_lo_u32 v86, v60, s0
	v_mul_lo_u32 v88, v64, s0
	v_cmp_ge_u32_e32 vcc, v79, v15
	v_cmp_lt_u32_e64 s[0:1], v79, v0
	v_or_b32_e32 v78, 17, v58
	v_readlane_b32 s22, v252, 39
	v_readlane_b32 s23, v252, 40
	s_addc_u32 s55, s13, s9
	v_add_u32_e32 v109, 0x100, v228
	v_min_u32_e32 v109, 0x1d0, v109
	v_lshlrev_b32_e32 v110, 2, v228
	v_lshlrev_b32_e32 v109, 2, v109
	global_load_dword v108, v110, s[54:55]
	global_load_dword v109, v109, s[54:55]
	s_and_b64 s[24:25], vcc, s[0:1]
	v_cmp_ge_u32_e32 vcc, v78, v15
	v_cmp_lt_u32_e64 s[0:1], v78, v0
	v_or_b32_e32 v77, 18, v58
	v_readlane_b32 s20, v252, 37
	v_readlane_b32 s21, v252, 38
	s_and_b64 s[22:23], vcc, s[0:1]
	v_cmp_ge_u32_e32 vcc, v77, v15
	v_cmp_lt_u32_e64 s[0:1], v77, v0
	v_or_b32_e32 v76, 19, v58
	v_readlane_b32 s18, v252, 35
	v_readlane_b32 s19, v252, 36
	s_and_b64 s[20:21], vcc, s[0:1]
	v_cmp_ge_u32_e32 vcc, v76, v15
	v_cmp_lt_u32_e64 s[0:1], v76, v0
	v_or_b32_e32 v75, 32, v58
	v_readlane_b32 s16, v252, 33
	v_readlane_b32 s17, v252, 34
	s_and_b64 s[18:19], vcc, s[0:1]
	v_cmp_ge_u32_e32 vcc, v75, v15
	v_cmp_lt_u32_e64 s[0:1], v75, v0
	v_or_b32_e32 v74, 33, v58
	v_readlane_b32 s14, v252, 31
	v_readlane_b32 s15, v252, 32
	s_and_b64 s[16:17], vcc, s[0:1]
	v_cmp_ge_u32_e32 vcc, v74, v15
	v_cmp_lt_u32_e64 s[0:1], v74, v0
	v_or_b32_e32 v73, 34, v58
	v_lshlrev_b32_e32 v84, 3, v11
	v_bfe_u32 v1, v10, 2, 2
	s_and_b64 s[14:15], vcc, s[0:1]
	v_cmp_ge_u32_e32 vcc, v73, v15
	v_cmp_lt_u32_e64 s[0:1], v73, v0
	v_or_b32_e32 v72, 35, v58
	v_or_b32_e32 v1, v84, v1
	s_and_b64 s[12:13], vcc, s[0:1]
	v_cmp_ge_u32_e32 vcc, v72, v15
	v_cmp_lt_u32_e64 s[0:1], v72, v0
	v_or_b32_e32 v71, 48, v58
	v_or_b32_e32 v70, 49, v58
	v_or_b32_e32 v69, 50, v58
	v_or_b32_e32 v68, 51, v58
	v_and_b32_e32 v12, 15, v10
	s_and_b64 s[10:11], vcc, s[0:1]
	v_cmp_lt_u32_e64 s[8:9], v71, v0
	v_cmp_lt_u32_e64 s[6:7], v70, v0
	v_cmp_lt_u32_e64 s[4:5], v69, v0
	v_cmp_lt_u32_e64 s[40:41], v68, v0
	v_mul_u32_u24_e32 v6, 0x90, v1
	v_mad_u64_u32 v[0:1], s[0:1], v80, 31, v[58:59]
	v_lshlrev_b32_e32 v2, 3, v10
	v_lshlrev_b32_e32 v3, 4, v60
	v_lshlrev_b32_e32 v4, 4, v64
	v_sub_u32_e32 v0, v0, v12
	v_readlane_b32 s26, v252, 43
	v_readlane_b32 s27, v252, 44
	v_and_b32_e32 v2, 24, v2
	v_lshlrev_b32_e32 v87, 4, v40
	v_lshlrev_b32_e32 v89, 4, v41
	v_sub_u32_e32 v3, v86, v3
	v_sub_u32_e32 v4, v88, v4
	v_mul_u32_u24_e32 v5, 0xa0, v12
	v_or_b32_e32 v83, 1, v58
	v_or_b32_e32 v82, 2, v58
	v_or_b32_e32 v81, 3, v58
	v_sub_u32_e32 v0, v0, v13
	s_mul_i32 s0, s3, 31
	v_mov_b32_e32 v8, v197
	v_mov_b32_e32 v9, v197
	v_mov_b32_e32 v10, v197
	v_mov_b32_e32 v11, v197
	v_cmp_lt_u32_e64 s[34:35], v58, v15
	v_cmp_lt_u32_e64 s[30:31], v83, v15
	v_cmp_lt_u32_e64 s[28:29], v82, v15
	v_cmp_lt_u32_e64 s[26:27], v81, v15
	v_subrev_u32_e32 v91, s0, v0
	v_add_u32_e32 v92, v3, v87
	v_add_u32_e32 v93, v4, v89
	v_add_u32_e32 v90, v196, v5
	v_add_u32_e32 v61, v2, v6
	v_mov_b64_e32 v[0:1], v[8:9]
	v_mov_b64_e32 v[4:5], v[8:9]
	v_mov_b64_e32 v[14:15], v[10:11]
	s_mov_b32 s72, 0xf149f2ca
	v_ashrrev_i32_e32 v57, 31, v56
	s_mov_b32 s97, 0
	v_mov_b32_e32 v59, 0
	v_mov_b32_e32 v65, 0xf149f2ca
	s_mov_b32 s42, -7
	v_mov_b64_e32 v[2:3], v[10:11]
	v_mov_b64_e32 v[6:7], v[10:11]
	v_mov_b64_e32 v[12:13], v[8:9]
	s_mov_b32 s43, 0
	s_branch .LBB0_454

.LBB0_454:
	v_add_co_u32_e64 v40, s[36:37], s42, 7
	s_add_i32 s43, s43, 1
	s_mov_b64 s[0:1], 0x200
	v_add_u32_e32 v94, v86, v87
	v_add_u32_e32 v95, v88, v89
	s_and_b64 vcc, exec, s[36:37]
	s_mov_b32 s1, s43
	s_mov_b64 s[36:37], s[56:57]
	s_mov_b64 s[58:59], s[64:65]
	s_waitcnt vmcnt(63) expcnt(7) lgkmcnt(15)
	s_barrier
	s_waitcnt vmcnt(3)
	ds_write_b128 v94, v[28:31]
	s_waitcnt vmcnt(2)
	ds_write_b128 v95, v[24:27]
	s_waitcnt vmcnt(1)
	ds_write_b128 v92, v[36:39] offset:10240
	s_waitcnt vmcnt(0)
	ds_write_b128 v93, v[32:35] offset:10240
	ds_write_b32 v110, v108 offset:32768
	ds_write_b32 v110, v109 offset:33792
	s_waitcnt lgkmcnt(0)
	s_barrier
	s_cbranch_vccnz .LBB0_456
	s_mov_b64 s[0:1], 0xd00
	s_mov_b32 s1, s42
	s_mov_b64 s[36:37], s[60:61]
	s_mov_b64 s[58:59], s[62:63]
.LBB0_456:
	s_lshl_b32 s2, s96, 1
	s_add_u32 vcc_lo, s58, s2
	s_addc_u32 vcc_hi, s59, 0
	s_add_u32 s58, s36, s2
	s_addc_u32 s59, s37, 0
	s_mul_hi_u32 s37, s1, s0
	s_mul_i32 s36, s1, s0
	s_lshl_b64 s[36:37], s[36:37], 7
	s_add_u32 s58, s58, s36
	s_addc_u32 s59, s59, s37
	s_add_u32 s36, vcc_lo, s36
	s_addc_u32 s37, vcc_hi, s37
	v_mad_i64_i32 v[24:25], vcc, s0, v60, 0
	v_mad_i64_i32 v[26:27], s[0:1], s0, v64, 0
	v_lshlrev_b64 v[32:33], 1, v[24:25]
	v_lshlrev_b64 v[34:35], 1, v[26:27]
	v_lshl_add_u64 v[24:25], s[58:59], 0, v[32:33]
	v_lshl_add_u64 v[26:27], s[58:59], 0, v[34:35]
	v_lshl_add_u64 v[32:33], s[36:37], 0, v[32:33]
	v_lshl_add_u64 v[34:35], s[36:37], 0, v[34:35]
	v_lshl_add_u64 v[24:25], v[24:25], 0, v[62:63]
	v_lshl_add_u64 v[26:27], v[26:27], 0, v[66:67]
	v_lshl_add_u64 v[32:33], v[32:33], 0, v[62:63]
	v_lshl_add_u64 v[34:35], v[34:35], 0, v[66:67]
	global_load_dwordx4 v[28:31], v[24:25], off
	s_nop 0
	global_load_dwordx4 v[24:27], v[26:27], off
	s_nop 0
	global_load_dwordx4 v[36:39], v[32:33], off
	s_nop 0
	global_load_dwordx4 v[32:35], v[34:35], off
	ds_read_b128 v[42:45], v90
	ds_read_b128 v[46:49], v90 offset:64
	ds_read_b128 v[50:53], v90 offset:2560
	ds_read_b128 v[96:99], v90 offset:2624
	v_cmp_lt_u32_e64 s[0:1], 7, v40
	v_cmp_gt_u32_e32 vcc, 8, v40
	s_waitcnt lgkmcnt(3)
	v_mfma_f32_16x16x32_bf16 v[42:45], v[42:45], v[20:23], 0
	s_and_b64 vcc, exec, vcc
	ds_read_b128 v[104:107], v90 offset:7744
	s_waitcnt lgkmcnt(2)
	v_mfma_f32_16x16x32_bf16 v[100:103], v[50:53], v[20:23], 0
	v_mfma_f32_16x16x32_bf16 v[52:55], v[46:49], v[16:19], v[42:45]
	s_nop 2
	ds_read_b128 v[42:45], v90 offset:5120
	s_waitcnt lgkmcnt(2)
	v_mfma_f32_16x16x32_bf16 v[48:51], v[96:99], v[16:19], v[100:103]
	ds_read_b128 v[96:99], v90 offset:5184
	s_nop 0
	v_mul_f32_e32 v52, 0x3e38aa3b, v52
	ds_read_b128 v[100:103], v90 offset:7680
	s_waitcnt lgkmcnt(2)
	v_mfma_f32_16x16x32_bf16 v[42:45], v[42:45], v[20:23], 0
	s_waitcnt lgkmcnt(1)
	v_mfma_f32_16x16x32_bf16 v[44:47], v[96:99], v[16:19], v[42:45]
	v_add_u32_e32 v96, s97, v91
	s_waitcnt lgkmcnt(0)
	v_mfma_f32_16x16x32_bf16 v[98:101], v[100:103], v[20:23], 0
	v_mfma_f32_16x16x32_bf16 v[40:43], v[104:107], v[16:19], v[98:101]
	s_cbranch_vccnz .LBB0_458
	v_add_u32_e32 v97, 0xffffff74, v96
	s_nop 4
	v_cndmask_b32_e64 v98, v97, 0, s[34:35]
	v_ashrrev_i32_e32 v99, 31, v98
	v_lshlrev_b32_e32 v98, 2, v98
	ds_read_b32 v97, v98 offset:32768
	s_waitcnt lgkmcnt(0)
	v_fmac_f32_e32 v52, 0x3fb8aa3b, v97
	v_cndmask_b32_e64 v52, v52, v235, s[34:35]
.LBB0_458:
	v_cndmask_b32_e64 v97, 0, 1, s[0:1]
	v_cmp_ne_u32_e64 s[36:37], 1, v97
	s_andn2_b64 vcc, exec, s[0:1]
	v_mul_f32_e32 v53, 0x3e38aa3b, v53
	s_cbranch_vccnz .LBB0_476
	v_add_u32_e32 v97, 0xffffff75, v96
	v_cndmask_b32_e64 v98, v97, 0, s[30:31]
	v_ashrrev_i32_e32 v99, 31, v98
	v_lshlrev_b32_e32 v98, 2, v98
	ds_read_b32 v97, v98 offset:32768
	s_waitcnt lgkmcnt(0)
	v_fmac_f32_e32 v53, 0x3fb8aa3b, v97
	v_cndmask_b32_e64 v53, v53, v235, s[30:31]
	s_and_b64 vcc, exec, s[36:37]
	v_mul_f32_e32 v54, 0x3e38aa3b, v54
	s_cbranch_vccz .LBB0_477

.LBB0_461:
	v_add_u32_e32 v97, 0xffffff77, v96
	v_cndmask_b32_e64 v98, v97, 0, s[26:27]
	v_ashrrev_i32_e32 v99, 31, v98
	v_lshlrev_b32_e32 v98, 2, v98
	ds_read_b32 v97, v98 offset:32768
	s_waitcnt lgkmcnt(0)
	v_fmac_f32_e32 v55, 0x3fb8aa3b, v97
	v_cndmask_b32_e64 v55, v55, v235, s[26:27]
	s_and_b64 vcc, exec, s[36:37]
	v_mul_f32_e32 v48, 0x3e38aa3b, v48
	s_cbranch_vccz .LBB0_479

.LBB0_463:
	v_add_u32_e32 v97, 0xffffff85, v96
	v_ashrrev_i32_e32 v98, 31, v97
	v_cndmask_b32_e64 v99, 0, v98, s[22:23]
	v_cndmask_b32_e64 v98, 0, v97, s[22:23]
	v_lshlrev_b32_e32 v98, 2, v98
	ds_read_b32 v97, v98 offset:32768
	s_waitcnt lgkmcnt(0)
	v_fmac_f32_e32 v49, 0x3fb8aa3b, v97
	v_cndmask_b32_e64 v49, v235, v49, s[22:23]
	s_and_b64 vcc, exec, s[36:37]
	v_mul_f32_e32 v50, 0x3e38aa3b, v50
	s_cbranch_vccz .LBB0_481

.LBB0_465:
	v_add_u32_e32 v97, 0xffffff87, v96
	v_ashrrev_i32_e32 v98, 31, v97
	v_cndmask_b32_e64 v99, 0, v98, s[18:19]
	v_cndmask_b32_e64 v98, 0, v97, s[18:19]
	v_lshlrev_b32_e32 v98, 2, v98
	ds_read_b32 v97, v98 offset:32768
	s_waitcnt lgkmcnt(0)
	v_fmac_f32_e32 v51, 0x3fb8aa3b, v97
	v_cndmask_b32_e64 v51, v235, v51, s[18:19]
	s_and_b64 vcc, exec, s[36:37]
	v_mul_f32_e32 v44, 0x3e38aa3b, v44
	s_cbranch_vccz .LBB0_483

.LBB0_467:
	v_add_u32_e32 v97, 0xffffff95, v96
	v_ashrrev_i32_e32 v98, 31, v97
	v_cndmask_b32_e64 v99, 0, v98, s[14:15]
	v_cndmask_b32_e64 v98, 0, v97, s[14:15]
	v_lshlrev_b32_e32 v98, 2, v98
	ds_read_b32 v97, v98 offset:32768
	s_waitcnt lgkmcnt(0)
	v_fmac_f32_e32 v45, 0x3fb8aa3b, v97
	v_cndmask_b32_e64 v45, v235, v45, s[14:15]
	s_and_b64 vcc, exec, s[36:37]
	v_mul_f32_e32 v46, 0x3e38aa3b, v46
	s_cbranch_vccz .LBB0_485

.LBB0_469:
	v_add_u32_e32 v47, 0xffffff97, v96
	v_ashrrev_i32_e32 v98, 31, v47
	v_cndmask_b32_e64 v99, 0, v98, s[10:11]
	v_cndmask_b32_e64 v98, 0, v47, s[10:11]
	v_lshlrev_b32_e32 v98, 2, v98
	ds_read_b32 v47, v98 offset:32768
	s_waitcnt lgkmcnt(0)
	v_fmac_f32_e32 v97, 0x3fb8aa3b, v47
	v_cndmask_b32_e64 v97, v235, v97, s[10:11]
	s_and_b64 vcc, exec, s[36:37]
	v_mul_f32_e32 v47, 0x3e38aa3b, v40
	s_cbranch_vccz .LBB0_487

.LBB0_471:
	v_add_u32_e32 v40, 0xffffffa5, v96
	v_cndmask_b32_e64 v98, 0, v40, s[6:7]
	v_ashrrev_i32_e32 v99, 31, v98
	v_lshlrev_b32_e32 v98, 2, v98
	ds_read_b32 v40, v98 offset:32768
	s_waitcnt lgkmcnt(0)
	v_fmac_f32_e32 v41, 0x3fb8aa3b, v40
	v_cndmask_b32_e64 v41, v235, v41, s[6:7]
	s_and_b64 vcc, exec, s[36:37]
	v_mul_f32_e32 v42, 0x3e38aa3b, v42
	s_cbranch_vccz .LBB0_489

.LBB0_473:
	v_add_u32_e32 v40, 0xffffffa7, v96
	v_cndmask_b32_e64 v98, 0, v40, s[40:41]
	v_ashrrev_i32_e32 v99, 31, v98
	v_lshlrev_b32_e32 v98, 2, v98
	ds_read_b32 v40, v98 offset:32768
	s_waitcnt lgkmcnt(0)
	v_fmac_f32_e32 v43, 0x3fb8aa3b, v40
	v_cndmask_b32_e64 v43, v235, v43, s[40:41]

.LBB0_477:
	v_add_u32_e32 v97, 0xffffff76, v96
	v_cndmask_b32_e64 v98, v97, 0, s[28:29]
	v_ashrrev_i32_e32 v99, 31, v98
	v_lshlrev_b32_e32 v98, 2, v98
	ds_read_b32 v97, v98 offset:32768
	s_waitcnt lgkmcnt(0)
	v_fmac_f32_e32 v54, 0x3fb8aa3b, v97
	v_cndmask_b32_e64 v54, v54, v235, s[28:29]
	s_and_b64 vcc, exec, s[36:37]
	v_mul_f32_e32 v55, 0x3e38aa3b, v55
	s_cbranch_vccz .LBB0_461

.LBB0_479:
	v_add_u32_e32 v97, 0xffffff84, v96
	v_ashrrev_i32_e32 v98, 31, v97
	v_cndmask_b32_e64 v99, 0, v98, s[24:25]
	v_cndmask_b32_e64 v98, 0, v97, s[24:25]
	v_lshlrev_b32_e32 v98, 2, v98
	ds_read_b32 v97, v98 offset:32768
	s_waitcnt lgkmcnt(0)
	v_fmac_f32_e32 v48, 0x3fb8aa3b, v97
	v_cndmask_b32_e64 v48, v235, v48, s[24:25]
	s_and_b64 vcc, exec, s[36:37]
	v_mul_f32_e32 v49, 0x3e38aa3b, v49
	s_cbranch_vccz .LBB0_463

.LBB0_481:
	v_add_u32_e32 v97, 0xffffff86, v96
	v_ashrrev_i32_e32 v98, 31, v97
	v_cndmask_b32_e64 v99, 0, v98, s[20:21]
	v_cndmask_b32_e64 v98, 0, v97, s[20:21]
	v_lshlrev_b32_e32 v98, 2, v98
	ds_read_b32 v97, v98 offset:32768
	s_waitcnt lgkmcnt(0)
	v_fmac_f32_e32 v50, 0x3fb8aa3b, v97
	v_cndmask_b32_e64 v50, v235, v50, s[20:21]
	s_and_b64 vcc, exec, s[36:37]
	v_mul_f32_e32 v51, 0x3e38aa3b, v51
	s_cbranch_vccz .LBB0_465

.LBB0_483:
	v_add_u32_e32 v97, 0xffffff94, v96
	v_ashrrev_i32_e32 v98, 31, v97
	v_cndmask_b32_e64 v99, 0, v98, s[16:17]
	v_cndmask_b32_e64 v98, 0, v97, s[16:17]
	v_lshlrev_b32_e32 v98, 2, v98
	ds_read_b32 v97, v98 offset:32768
	s_waitcnt lgkmcnt(0)
	v_fmac_f32_e32 v44, 0x3fb8aa3b, v97
	v_cndmask_b32_e64 v44, v235, v44, s[16:17]
	s_and_b64 vcc, exec, s[36:37]
	v_mul_f32_e32 v45, 0x3e38aa3b, v45
	s_cbranch_vccz .LBB0_467

.LBB0_485:
	v_add_u32_e32 v97, 0xffffff96, v96
	v_ashrrev_i32_e32 v98, 31, v97
	v_cndmask_b32_e64 v99, 0, v98, s[12:13]
	v_cndmask_b32_e64 v98, 0, v97, s[12:13]
	v_lshlrev_b32_e32 v98, 2, v98
	ds_read_b32 v97, v98 offset:32768
	s_waitcnt lgkmcnt(0)
	v_fmac_f32_e32 v46, 0x3fb8aa3b, v97
	v_cndmask_b32_e64 v46, v235, v46, s[12:13]
	s_and_b64 vcc, exec, s[36:37]
	v_mul_f32_e32 v97, 0x3e38aa3b, v47
	s_cbranch_vccz .LBB0_469

.LBB0_487:
	v_add_u32_e32 v40, 0xffffffa4, v96
	v_cndmask_b32_e64 v98, 0, v40, s[8:9]
	v_ashrrev_i32_e32 v99, 31, v98
	v_lshlrev_b32_e32 v98, 2, v98
	ds_read_b32 v40, v98 offset:32768
	s_waitcnt lgkmcnt(0)
	v_fmac_f32_e32 v47, 0x3fb8aa3b, v40
	v_cndmask_b32_e64 v47, v235, v47, s[8:9]
	s_and_b64 vcc, exec, s[36:37]
	v_mul_f32_e32 v41, 0x3e38aa3b, v41
	s_cbranch_vccz .LBB0_471

.LBB0_489:
	v_add_u32_e32 v40, 0xffffffa6, v96
	v_cndmask_b32_e64 v98, 0, v40, s[4:5]
	v_ashrrev_i32_e32 v99, 31, v98
	v_lshlrev_b32_e32 v98, 2, v98
	ds_read_b32 v40, v98 offset:32768
	s_waitcnt lgkmcnt(0)
	v_fmac_f32_e32 v42, 0x3fb8aa3b, v40
	v_cndmask_b32_e64 v42, v235, v42, s[4:5]
	s_and_b64 vcc, exec, s[36:37]
	v_mul_f32_e32 v43, 0x3e38aa3b, v43
	s_cbranch_vccz .LBB0_473
	s_branch .LBB0_474
